# v13
# speedup vs baseline: 1.0052x; 1.0044x over previous
; __device__ __forceinline__ float bflo(unsigned w) { return __uint_as_float(w << 16); }
; __device__ __forceinline__ float bfhi(unsigned w) { return __uint_as_float(w & 0xffff0000u); }
; __device__ __forceinline__ void phase_sgu(const Params& p, char* shm) {
;     ...
;       unsigned ao = (unsigned)(chunk * 131072 + g * 16384 + (half * 32 + fr) * 128 + fq * 8); asm volatile("" : "+v"(ao));
;       const int cbase = g * 128 + half * 32 + fq * 4;
;       unsigned eo = (unsigned)(fr * DM + cbase); asm volatile("" : "+v"(eo));
;       u32x4 araw[4][2];
; #pragma unroll
;       for (int ks = 0; ks < 4; ++ks)
; #pragma unroll
;         for (int mb = 0; mb < 2; ++mb) araw[ks][mb] = *(const u32x4*)(vsT + (ao + (unsigned)(mb * 16 * 128 + ks * 32)));
;       u32x2 uw0[8], gw0[8], uw1[8], gw1[8];
; #pragma unroll
;       for (int nb = 0; nb < 8; ++nb) { const unsigned idx = eo + (unsigned)(nb * 16 * DM);
;         uw0[nb] = *(const u32x2*)(ubc + idx); gw0[nb] = *(const u32x2*)(gbc + idx); uw1[nb] = *(const u32x2*)(ubc + idx + 16); gw1[nb] = *(const u32x2*)(gbc + idx + 16); }
;       unsigned lo_ = (unsigned)(g4 * 32768 + fr * 256 + ((fq * 16) ^ (fr << 4))); asm volatile("" : "+v"(lo_));
; #pragma unroll
;       for (int ks = 0; ks < 4; ++ks) {
;         bf16x8 a[2];
; #pragma unroll
;         for (int mb = 0; mb < 2; ++mb) {
;           const u32x4 w = araw[ks][mb];
;           u32x4 o = {cvtpk(bflo(w[0]) * sc[ks][0], bfhi(w[0]) * sc[ks][1]), cvtpk(bflo(w[1]) * sc[ks][2], bfhi(w[1]) * sc[ks][3]),
;                      cvtpk(bflo(w[2]) * sc[ks][4], bfhi(w[2]) * sc[ks][5]), cvtpk(bflo(w[3]) * sc[ks][6], bfhi(w[3]) * sc[ks][7])};
;           a[mb] = *reinterpret_cast<bf16x8*>(&o);
;         }
; #pragma unroll
;         for (int nh = 0; nh < 2; ++nh) {
;           bf16x8 b[4];
; #pragma unroll
;           for (int nb = 0; nb < 4; ++nb) b[nb] = *(const bf16x8*)(shm + ((lo_ ^ (unsigned)(ks << 6)) + (unsigned)((nh * 4 + nb) * 4096)));
; #pragma unroll
;           for (int mb = 0; mb < 2; ++mb)
; #pragma unroll
;             for (int nb = 0; nb < 4; ++nb) acc[mb][nh * 4 + nb] = __builtin_amdgcn_mfma_f32_16x16x32_bf16(a[mb], b[nb], acc[mb][nh * 4 + nb], 0, 0, 0);
.LBB0_217:
	v_mov_b32_e32 v72, v191
	v_add_u32_e32 v40, v183, v190
	v_lshl_add_u64 v[0:1], v[72:73], 1, s[62:63]
	v_add_u32_e32 v2, 0x800, v72
	v_mov_b32_e32 v3, v73
	v_lshl_add_u64 v[2:3], v[2:3], 1, s[62:63]
	global_load_dwordx4 v[20:23], v[0:1], off
	global_load_dwordx4 v[32:35], v[2:3], off
	v_add_u32_e32 v0, 32, v72
	v_mov_b32_e32 v1, v73
	v_lshl_add_u64 v[0:1], v[0:1], 1, s[62:63]
	v_add_u32_e32 v2, 0x820, v72
	v_mov_b32_e32 v3, v73
	v_lshl_add_u64 v[2:3], v[2:3], 1, s[62:63]
	global_load_dwordx4 v[36:39], v[0:1], off
	global_load_dwordx4 v[16:19], v[2:3], off
	v_add_u32_e32 v0, 64, v72
	v_mov_b32_e32 v1, v73
	v_lshl_add_u64 v[0:1], v[0:1], 1, s[62:63]
	v_add_u32_e32 v2, 0x840, v72
	v_mov_b32_e32 v3, v73
	v_mov_b32_e32 v41, v73
	v_lshl_add_u64 v[2:3], v[2:3], 1, s[62:63]
	global_load_dwordx4 v[12:15], v[0:1], off
	global_load_dwordx4 v[8:11], v[2:3], off
	v_add_u32_e32 v0, 0x60, v72
	v_mov_b32_e32 v1, v73
	v_add_u32_e32 v72, 0x860, v72
	v_lshlrev_b64 v[24:25], 1, v[40:41]
	v_lshl_add_u64 v[0:1], v[0:1], 1, s[62:63]
	v_lshl_add_u64 v[2:3], v[72:73], 1, s[62:63]
	v_lshl_add_u64 v[26:27], s[6:7], 0, v[24:25]
	v_lshl_add_u64 v[24:25], s[8:9], 0, v[24:25]
	v_add_u32_e32 v72, 0x4000, v40
	global_load_dwordx4 v[4:7], v[0:1], off
	s_nop 0
	global_load_dwordx4 v[0:3], v[2:3], off
	s_nop 0
	global_load_dwordx2 v[172:173], v[26:27], off
	global_load_dwordx2 v[174:175], v[24:25], off
	global_load_dwordx2 v[170:171], v[24:25], off offset:32
	global_load_dwordx2 v[168:169], v[26:27], off offset:32
	v_lshlrev_b64 v[24:25], 1, v[72:73]
	v_lshl_add_u64 v[26:27], s[6:7], 0, v[24:25]
	v_lshl_add_u64 v[24:25], s[8:9], 0, v[24:25]
	v_add_u32_e32 v72, 0x8000, v40
	global_load_dwordx2 v[162:163], v[26:27], off
	global_load_dwordx2 v[164:165], v[24:25], off
	global_load_dwordx2 v[160:161], v[24:25], off offset:32
	global_load_dwordx2 v[158:159], v[26:27], off offset:32
	v_lshlrev_b64 v[24:25], 1, v[72:73]
	v_lshl_add_u64 v[42:43], s[6:7], 0, v[24:25]
	v_lshl_add_u64 v[24:25], s[8:9], 0, v[24:25]
	v_add_u32_e32 v72, 0xc000, v40
	global_load_dwordx2 v[28:29], v[42:43], off
	global_load_dwordx2 v[30:31], v[24:25], off
	global_load_dwordx2 v[26:27], v[24:25], off offset:32
	s_nop 0
	global_load_dwordx2 v[24:25], v[42:43], off offset:32
	v_lshlrev_b64 v[42:43], 1, v[72:73]
	v_lshl_add_u64 v[44:45], s[6:7], 0, v[42:43]
	v_lshl_add_u64 v[42:43], s[8:9], 0, v[42:43]
	v_add_u32_e32 v72, 0x10000, v40
	global_load_dwordx2 v[154:155], v[44:45], off
	global_load_dwordx2 v[156:157], v[42:43], off
	global_load_dwordx2 v[152:153], v[42:43], off offset:32
	global_load_dwordx2 v[150:151], v[44:45], off offset:32
	v_lshlrev_b64 v[42:43], 1, v[72:73]
	v_lshl_add_u64 v[44:45], s[6:7], 0, v[42:43]
	v_lshl_add_u64 v[42:43], s[8:9], 0, v[42:43]
	v_add_u32_e32 v72, 0x14000, v40
	global_load_dwordx2 v[146:147], v[44:45], off
	global_load_dwordx2 v[148:149], v[42:43], off
	global_load_dwordx2 v[144:145], v[42:43], off offset:32
	global_load_dwordx2 v[142:143], v[44:45], off offset:32
	v_lshlrev_b64 v[42:43], 1, v[72:73]
	v_lshl_add_u64 v[44:45], s[6:7], 0, v[42:43]
	v_lshl_add_u64 v[42:43], s[8:9], 0, v[42:43]
	v_add_u32_e32 v72, 0x18000, v40
	global_load_dwordx2 v[138:139], v[44:45], off
	global_load_dwordx2 v[140:141], v[42:43], off
	global_load_dwordx2 v[136:137], v[42:43], off offset:32
	global_load_dwordx2 v[134:135], v[44:45], off offset:32
	v_lshlrev_b64 v[42:43], 1, v[72:73]
	v_add_u32_e32 v72, 0x1c000, v40
	v_lshl_add_u64 v[44:45], s[6:7], 0, v[42:43]
	v_lshl_add_u64 v[42:43], s[8:9], 0, v[42:43]
	v_lshlrev_b64 v[40:41], 1, v[72:73]
	global_load_dwordx2 v[130:131], v[44:45], off
	global_load_dwordx2 v[132:133], v[42:43], off
	global_load_dwordx2 v[128:129], v[42:43], off offset:32
	global_load_dwordx2 v[126:127], v[44:45], off offset:32
	v_lshl_add_u64 v[42:43], s[6:7], 0, v[40:41]
	v_lshl_add_u64 v[40:41], s[8:9], 0, v[40:41]
	global_load_dwordx2 v[122:123], v[42:43], off
	global_load_dwordx2 v[124:125], v[40:41], off
	global_load_dwordx2 v[120:121], v[40:41], off offset:32
	global_load_dwordx2 v[118:119], v[42:43], off offset:32
	v_mov_b32_e32 v72, v179
	ds_read_b128 v[52:55], v72 offset:8192
	s_waitcnt vmcnt(39)
	v_lshlrev_b32_e32 v40, 16, v20
	v_and_b32_e32 v41, 0xffff0000, v20
	v_pk_mul_f32 v[40:41], v[82:83], v[40:41]
	s_waitcnt vmcnt(38)
	v_lshlrev_b32_e32 v44, 16, v33
	v_cvt_pk_bf16_f32 v20, v40, v41
	v_lshlrev_b32_e32 v40, 16, v21
	v_and_b32_e32 v41, 0xffff0000, v21
	v_pk_mul_f32 v[40:41], v[84:85], v[40:41]
	v_and_b32_e32 v45, 0xffff0000, v33
	v_cvt_pk_bf16_f32 v21, v40, v41
	v_lshlrev_b32_e32 v40, 16, v22
	v_and_b32_e32 v41, 0xffff0000, v22
	v_pk_mul_f32 v[40:41], v[86:87], v[40:41]
	v_lshlrev_b32_e32 v60, 16, v34
	v_cvt_pk_bf16_f32 v22, v40, v41
	v_lshlrev_b32_e32 v40, 16, v23
	v_and_b32_e32 v41, 0xffff0000, v23
	v_pk_mul_f32 v[40:41], v[88:89], v[40:41]
	v_and_b32_e32 v61, 0xffff0000, v34
	v_cvt_pk_bf16_f32 v23, v40, v41
	v_lshlrev_b32_e32 v40, 16, v32
	v_and_b32_e32 v41, 0xffff0000, v32
	v_lshlrev_b32_e32 v68, 16, v35
	v_and_b32_e32 v69, 0xffff0000, v35
	v_pk_mul_f32 v[40:41], v[82:83], v[40:41]
	v_pk_mul_f32 v[44:45], v[84:85], v[44:45]
	v_pk_mul_f32 v[60:61], v[86:87], v[60:61]
	v_pk_mul_f32 v[166:167], v[88:89], v[68:69]
	v_cvt_pk_bf16_f32 v32, v40, v41
	ds_read_b128 v[40:43], v72
	v_cvt_pk_bf16_f32 v33, v44, v45
	ds_read_b128 v[44:47], v72 offset:4096
	v_cvt_pk_bf16_f32 v34, v60, v61
	ds_read_b128 v[60:63], v72 offset:12288
	v_cvt_pk_bf16_f32 v35, v166, v167
	s_waitcnt lgkmcnt(2)
	v_mfma_f32_16x16x32_bf16 v[48:51], v[20:23], v[40:43], 0
	v_add_u32_e32 v166, v183, v189
	s_waitcnt lgkmcnt(1)
; __device__ __forceinline__ float bflo(unsigned w) { return __uint_as_float(w << 16); }
; __device__ __forceinline__ float bfhi(unsigned w) { return __uint_as_float(w & 0xffff0000u); }
; #define SBAR() __builtin_amdgcn_sched_barrier(0)
; __device__ __forceinline__ void phase_sgu(const Params& p, char* shm) {
;     ...
;       for (int ks = 0; ks < 4; ++ks) {
;         bf16x8 a[2];
; #pragma unroll
;         for (int mb = 0; mb < 2; ++mb) {
;           const u32x4 w = araw[ks][mb];
;           u32x4 o = {cvtpk(bflo(w[0]) * sc[ks][0], bfhi(w[0]) * sc[ks][1]), cvtpk(bflo(w[1]) * sc[ks][2], bfhi(w[1]) * sc[ks][3]),
;                      cvtpk(bflo(w[2]) * sc[ks][4], bfhi(w[2]) * sc[ks][5]), cvtpk(bflo(w[3]) * sc[ks][6], bfhi(w[3]) * sc[ks][7])};
;           a[mb] = *reinterpret_cast<bf16x8*>(&o);
;         }
; #pragma unroll
;         for (int nh = 0; nh < 2; ++nh) {
;           bf16x8 b[4];
; #pragma unroll
;           for (int nb = 0; nb < 4; ++nb) b[nb] = *(const bf16x8*)(shm + ((lo_ ^ (unsigned)(ks << 6)) + (unsigned)((nh * 4 + nb) * 4096)));
; #pragma unroll
;           for (int mb = 0; mb < 2; ++mb)
; #pragma unroll
;             for (int nb = 0; nb < 4; ++nb) acc[mb][nh * 4 + nb] = __builtin_amdgcn_mfma_f32_16x16x32_bf16(a[mb], b[nb], acc[mb][nh * 4 + nb], 0, 0, 0);
;           SBAR();
	v_mfma_f32_16x16x32_bf16 v[56:59], v[20:23], v[44:47], 0
	v_mfma_f32_16x16x32_bf16 v[64:67], v[20:23], v[52:55], 0
	s_waitcnt lgkmcnt(0)
	v_mfma_f32_16x16x32_bf16 v[68:71], v[20:23], v[60:63], 0
	v_mfma_f32_16x16x32_bf16 v[40:43], v[32:35], v[40:43], 0
	v_mfma_f32_16x16x32_bf16 v[44:47], v[32:35], v[44:47], 0
	v_mfma_f32_16x16x32_bf16 v[52:55], v[32:35], v[52:55], 0
	v_mfma_f32_16x16x32_bf16 v[60:63], v[32:35], v[60:63], 0
	ds_read_b128 v[194:197], v72 offset:16384
	ds_read_b128 v[204:207], v72 offset:20480
	ds_read_b128 v[216:219], v72 offset:24576
	ds_read_b128 v[220:223], v72 offset:28672
	s_waitcnt lgkmcnt(3)
	v_mfma_f32_16x16x32_bf16 v[208:211], v[20:23], v[194:197], 0
	s_waitcnt lgkmcnt(2)
	v_mfma_f32_16x16x32_bf16 v[212:215], v[20:23], v[204:207], 0
	s_waitcnt lgkmcnt(1)
	v_mfma_f32_16x16x32_bf16 v[224:227], v[20:23], v[216:219], 0
	s_waitcnt lgkmcnt(0)
	v_mfma_f32_16x16x32_bf16 v[20:23], v[20:23], v[220:223], 0
	v_mfma_f32_16x16x32_bf16 v[194:197], v[32:35], v[194:197], 0
	v_mfma_f32_16x16x32_bf16 v[204:207], v[32:35], v[204:207], 0
	v_mfma_f32_16x16x32_bf16 v[216:219], v[32:35], v[216:219], 0
	v_mfma_f32_16x16x32_bf16 v[32:35], v[32:35], v[220:223], 0
	s_waitcnt vmcnt(37)
	v_lshlrev_b32_e32 v198, 16, v36
	v_and_b32_e32 v199, 0xffff0000, v36
	v_pk_mul_f32 v[198:199], v[90:91], v[198:199]
	v_xor_b32_e32 v167, 64, v72
	v_cvt_pk_bf16_f32 v36, v198, v199
	v_lshlrev_b32_e32 v198, 16, v37
	v_and_b32_e32 v199, 0xffff0000, v37
	v_pk_mul_f32 v[198:199], v[92:93], v[198:199]
	ds_read_b128 v[220:223], v167
	ds_read_b128 v[228:231], v167 offset:4096
	v_cvt_pk_bf16_f32 v37, v198, v199
	v_lshlrev_b32_e32 v198, 16, v38
	v_and_b32_e32 v199, 0xffff0000, v38
	v_pk_mul_f32 v[198:199], v[94:95], v[198:199]
	ds_read_b128 v[232:235], v167 offset:8192
	ds_read_b128 v[236:239], v167 offset:12288
	v_cvt_pk_bf16_f32 v38, v198, v199
	v_lshlrev_b32_e32 v198, 16, v39
	v_and_b32_e32 v199, 0xffff0000, v39
	v_pk_mul_f32 v[198:199], v[96:97], v[198:199]
	s_nop 0
	v_cvt_pk_bf16_f32 v39, v198, v199
	s_waitcnt vmcnt(36)
	v_lshlrev_b32_e32 v198, 16, v16
	v_and_b32_e32 v199, 0xffff0000, v16
	v_pk_mul_f32 v[198:199], v[90:91], v[198:199]
	s_waitcnt lgkmcnt(3)
	v_mfma_f32_16x16x32_bf16 v[48:51], v[36:39], v[220:223], v[48:51]
	v_cvt_pk_bf16_f32 v16, v198, v199
	v_lshlrev_b32_e32 v198, 16, v17
	v_and_b32_e32 v199, 0xffff0000, v17
	v_pk_mul_f32 v[198:199], v[92:93], v[198:199]
	s_waitcnt lgkmcnt(2)
	v_mfma_f32_16x16x32_bf16 v[56:59], v[36:39], v[228:231], v[56:59]
	v_cvt_pk_bf16_f32 v17, v198, v199
	v_lshlrev_b32_e32 v198, 16, v18
	v_and_b32_e32 v199, 0xffff0000, v18
	v_pk_mul_f32 v[198:199], v[94:95], v[198:199]
	s_waitcnt lgkmcnt(1)
	v_mfma_f32_16x16x32_bf16 v[64:67], v[36:39], v[232:235], v[64:67]
	v_cvt_pk_bf16_f32 v18, v198, v199
	v_lshlrev_b32_e32 v198, 16, v19
	v_and_b32_e32 v199, 0xffff0000, v19
	v_pk_mul_f32 v[198:199], v[96:97], v[198:199]
	s_waitcnt lgkmcnt(0)
	v_mfma_f32_16x16x32_bf16 v[68:71], v[36:39], v[236:239], v[68:71]
	v_cvt_pk_bf16_f32 v19, v198, v199
	s_nop 1
	v_mfma_f32_16x16x32_bf16 v[40:43], v[16:19], v[220:223], v[40:43]
	v_mfma_f32_16x16x32_bf16 v[44:47], v[16:19], v[228:231], v[44:47]
	v_mfma_f32_16x16x32_bf16 v[52:55], v[16:19], v[232:235], v[52:55]
	v_mfma_f32_16x16x32_bf16 v[60:63], v[16:19], v[236:239], v[60:63]
	ds_read_b128 v[220:223], v167 offset:16384
	ds_read_b128 v[228:231], v167 offset:20480
	ds_read_b128 v[232:235], v167 offset:24576
	ds_read_b128 v[236:239], v167 offset:28672
	s_waitcnt lgkmcnt(3)
	v_mfma_f32_16x16x32_bf16 v[208:211], v[36:39], v[220:223], v[208:211]
	s_waitcnt lgkmcnt(2)
	v_mfma_f32_16x16x32_bf16 v[212:215], v[36:39], v[228:231], v[212:215]
	s_waitcnt lgkmcnt(1)
	v_mfma_f32_16x16x32_bf16 v[224:227], v[36:39], v[232:235], v[224:227]
	s_waitcnt lgkmcnt(0)
	v_mfma_f32_16x16x32_bf16 v[20:23], v[36:39], v[236:239], v[20:23]
	v_mfma_f32_16x16x32_bf16 v[36:39], v[16:19], v[220:223], v[194:197]
	v_mfma_f32_16x16x32_bf16 v[194:197], v[16:19], v[228:231], v[204:207]
	v_mfma_f32_16x16x32_bf16 v[204:207], v[16:19], v[232:235], v[216:219]
	v_mfma_f32_16x16x32_bf16 v[16:19], v[16:19], v[236:239], v[32:35]
	s_waitcnt vmcnt(35)
	s_nop 1
	v_lshlrev_b32_e32 v32, 16, v12
	v_and_b32_e32 v33, 0xffff0000, v12
	v_pk_mul_f32 v[32:33], v[98:99], v[32:33]
	v_xor_b32_e32 v167, 0x80, v72
	v_cvt_pk_bf16_f32 v12, v32, v33
	v_lshlrev_b32_e32 v32, 16, v13
	v_and_b32_e32 v33, 0xffff0000, v13
	v_pk_mul_f32 v[32:33], v[100:101], v[32:33]
	ds_read_b128 v[220:223], v167 offset:8192
	ds_read_b128 v[228:231], v167 offset:12288
	v_cvt_pk_bf16_f32 v13, v32, v33
	v_lshlrev_b32_e32 v32, 16, v14
	v_and_b32_e32 v33, 0xffff0000, v14
	v_pk_mul_f32 v[32:33], v[102:103], v[32:33]
	s_waitcnt vmcnt(34)
	v_lshlrev_b32_e32 v198, 16, v9
	v_cvt_pk_bf16_f32 v14, v32, v33
	v_lshlrev_b32_e32 v32, 16, v15
	v_and_b32_e32 v33, 0xffff0000, v15
	v_pk_mul_f32 v[32:33], v[104:105], v[32:33]
	v_and_b32_e32 v199, 0xffff0000, v9
	v_cvt_pk_bf16_f32 v15, v32, v33
	v_pk_mul_f32 v[198:199], v[100:101], v[198:199]
	v_lshlrev_b32_e32 v32, 16, v8
	v_and_b32_e32 v33, 0xffff0000, v8
	v_cvt_pk_bf16_f32 v9, v198, v199
	v_lshlrev_b32_e32 v198, 16, v10
	v_and_b32_e32 v199, 0xffff0000, v10
	s_waitcnt lgkmcnt(1)
	v_mfma_f32_16x16x32_bf16 v[232:235], v[12:15], v[220:223], v[64:67]
	v_mul_f32_e64 v32, v98, v32
	v_mul_f32_e64 v33, v99, v33
	v_pk_mul_f32 v[198:199], v[102:103], v[198:199]
	v_cvt_pk_bf16_f32 v8, v32, v33
	v_lshlrev_b32_e32 v64, 16, v11
	v_and_b32_e32 v65, 0xffff0000, v11
	v_pk_mul_f32 v[64:65], v[104:105], v[64:65]
	ds_read_b128 v[32:35], v167
	ds_read_b128 v[216:219], v167 offset:4096
	v_cvt_pk_bf16_f32 v10, v198, v199
	v_cvt_pk_bf16_f32 v11, v64, v65
	s_waitcnt lgkmcnt(1)
; __device__ __forceinline__ float bflo(unsigned w) { return __uint_as_float(w << 16); }
; __device__ __forceinline__ float bfhi(unsigned w) { return __uint_as_float(w & 0xffff0000u); }
; #define SBAR() __builtin_amdgcn_sched_barrier(0)
; __device__ __forceinline__ u32x2 pk4(float a, float b, float c, float d) { return u32x2{cvtpk(a, b), cvtpk(c, d)}; }
; __device__ __forceinline__ void phase_sgu(const Params& p, char* shm) {
;     ...
;       for (int ks = 0; ks < 4; ++ks) {
;         bf16x8 a[2];
; #pragma unroll
;         for (int mb = 0; mb < 2; ++mb) {
;           const u32x4 w = araw[ks][mb];
;           u32x4 o = {cvtpk(bflo(w[0]) * sc[ks][0], bfhi(w[0]) * sc[ks][1]), cvtpk(bflo(w[1]) * sc[ks][2], bfhi(w[1]) * sc[ks][3]),
;                      cvtpk(bflo(w[2]) * sc[ks][4], bfhi(w[2]) * sc[ks][5]), cvtpk(bflo(w[3]) * sc[ks][6], bfhi(w[3]) * sc[ks][7])};
;           a[mb] = *reinterpret_cast<bf16x8*>(&o);
;         }
; #pragma unroll
;         for (int nh = 0; nh < 2; ++nh) {
;           bf16x8 b[4];
; #pragma unroll
;           for (int nb = 0; nb < 4; ++nb) b[nb] = *(const bf16x8*)(shm + ((lo_ ^ (unsigned)(ks << 6)) + (unsigned)((nh * 4 + nb) * 4096)));
; #pragma unroll
;           for (int mb = 0; mb < 2; ++mb)
; #pragma unroll
;             for (int nb = 0; nb < 4; ++nb) acc[mb][nh * 4 + nb] = __builtin_amdgcn_mfma_f32_16x16x32_bf16(a[mb], b[nb], acc[mb][nh * 4 + nb], 0, 0, 0);
;           SBAR();
;         }
;       }
;       const float4 gj0 = *(const float4*)(p.sgu_norm_g + cbase), gj1 = *(const float4*)(p.sgu_norm_g + cbase + 16);
; #pragma unroll
;       for (int nb = 0; nb < 8; ++nb) {
;         const int pp = nb * 16 + fr; const float bias = p.b_s[g * 128 + pp];
;         const u32x2 u0 = uw0[nb], g0 = gw0[nb], u1 = uw1[nb], g1 = gw1[nb];
;         const u32x2 o0 = pk4(bflo(g0[0]) * bflo(u0[0]) * (gj0.x * acc[0][nb][0] + bias), bfhi(g0[0]) * bfhi(u0[0]) * (gj0.y * acc[0][nb][1] + bias),
;                              bflo(g0[1]) * bflo(u0[1]) * (gj0.z * acc[0][nb][2] + bias), bfhi(g0[1]) * bfhi(u0[1]) * (gj0.w * acc[0][nb][3] + bias));
;         const u32x2 o1 = pk4(bflo(g1[0]) * bflo(u1[0]) * (gj1.x * acc[1][nb][0] + bias), bfhi(g1[0]) * bfhi(u1[0]) * (gj1.y * acc[1][nb][1] + bias),
;                              bflo(g1[1]) * bflo(u1[1]) * (gj1.z * acc[1][nb][2] + bias), bfhi(g1[1]) * bfhi(u1[1]) * (gj1.w * acc[1][nb][3] + bias));
	v_mfma_f32_16x16x32_bf16 v[48:51], v[12:15], v[32:35], v[48:51]
	s_waitcnt lgkmcnt(0)
	v_mfma_f32_16x16x32_bf16 v[56:59], v[12:15], v[216:219], v[56:59]
	v_mfma_f32_16x16x32_bf16 v[68:71], v[12:15], v[228:231], v[68:71]
	v_mfma_f32_16x16x32_bf16 v[32:35], v[8:11], v[32:35], v[40:43]
	v_mfma_f32_16x16x32_bf16 v[44:47], v[8:11], v[216:219], v[44:47]
	v_mfma_f32_16x16x32_bf16 v[52:55], v[8:11], v[220:223], v[52:55]
	v_mfma_f32_16x16x32_bf16 v[216:219], v[8:11], v[228:231], v[60:63]
	ds_read_b128 v[40:43], v167 offset:16384
	s_nop 1
	ds_read_b128 v[60:63], v167 offset:20480
	ds_read_b128 v[64:67], v167 offset:24576
	ds_read_b128 v[220:223], v167 offset:28672
	s_waitcnt lgkmcnt(3)
	v_mfma_f32_16x16x32_bf16 v[208:211], v[12:15], v[40:43], v[208:211]
	s_waitcnt lgkmcnt(2)
	v_mfma_f32_16x16x32_bf16 v[212:215], v[12:15], v[60:63], v[212:215]
	s_waitcnt lgkmcnt(1)
	v_mfma_f32_16x16x32_bf16 v[224:227], v[12:15], v[64:67], v[224:227]
	s_waitcnt lgkmcnt(0)
	v_mfma_f32_16x16x32_bf16 v[12:15], v[12:15], v[220:223], v[20:23]
	v_mfma_f32_16x16x32_bf16 v[20:23], v[8:11], v[40:43], v[36:39]
	v_mfma_f32_16x16x32_bf16 v[194:197], v[8:11], v[60:63], v[194:197]
	v_mfma_f32_16x16x32_bf16 v[204:207], v[8:11], v[64:67], v[204:207]
	v_mfma_f32_16x16x32_bf16 v[220:223], v[8:11], v[220:223], v[16:19]
	s_waitcnt vmcnt(33)
	v_lshlrev_b32_e32 v8, 16, v4
	v_and_b32_e32 v9, 0xffff0000, v4
	v_pk_mul_f32 v[8:9], v[106:107], v[8:9]
	v_xor_b32_e32 v72, 0xc0, v72
	v_cvt_pk_bf16_f32 v4, v8, v9
	v_lshlrev_b32_e32 v8, 16, v5
	v_and_b32_e32 v9, 0xffff0000, v5
	v_pk_mul_f32 v[8:9], v[108:109], v[8:9]
	ds_read_b128 v[36:39], v72 offset:8192
	ds_read_b128 v[236:239], v72 offset:12288
	v_cvt_pk_bf16_f32 v5, v8, v9
	v_lshlrev_b32_e32 v8, 16, v6
	v_and_b32_e32 v9, 0xffff0000, v6
	v_pk_mul_f32 v[8:9], v[110:111], v[8:9]
	ds_read_b128 v[16:19], v72 offset:4096
	v_cvt_pk_bf16_f32 v6, v8, v9
	v_lshlrev_b32_e32 v8, 16, v7
	v_and_b32_e32 v9, 0xffff0000, v7
	v_pk_mul_f32 v[8:9], v[112:113], v[8:9]
	s_nop 0
	v_cvt_pk_bf16_f32 v7, v8, v9
	s_waitcnt vmcnt(32)
	v_lshlrev_b32_e32 v8, 16, v0
	v_and_b32_e32 v9, 0xffff0000, v0
	v_lshlrev_b32_e32 v0, 16, v1
	v_and_b32_e32 v1, 0xffff0000, v1
	v_pk_mul_f32 v[0:1], v[108:109], v[0:1]
	v_pk_mul_f32 v[8:9], v[106:107], v[8:9]
	v_cvt_pk_bf16_f32 v229, v0, v1
	v_lshlrev_b32_e32 v0, 16, v2
	v_and_b32_e32 v1, 0xffff0000, v2
	v_pk_mul_f32 v[0:1], v[110:111], v[0:1]
	v_cvt_pk_bf16_f32 v228, v8, v9
	v_cvt_pk_bf16_f32 v230, v0, v1
	v_lshlrev_b32_e32 v0, 16, v3
	v_and_b32_e32 v1, 0xffff0000, v3
	v_pk_mul_f32 v[0:1], v[112:113], v[0:1]
	ds_read_b128 v[8:11], v72
	v_cvt_pk_bf16_f32 v231, v0, v1
	s_waitcnt lgkmcnt(0)
	v_mfma_f32_16x16x32_bf16 v[64:67], v[4:7], v[8:11], v[48:51]
	v_mfma_f32_16x16x32_bf16 v[56:59], v[4:7], v[16:19], v[56:59]
	v_mfma_f32_16x16x32_bf16 v[48:51], v[4:7], v[36:39], v[232:235]
	v_mfma_f32_16x16x32_bf16 v[40:43], v[4:7], v[236:239], v[68:71]
	v_mfma_f32_16x16x32_bf16 v[68:71], v[228:231], v[8:11], v[32:35]
	v_mfma_f32_16x16x32_bf16 v[60:63], v[228:231], v[16:19], v[44:47]
	v_mfma_f32_16x16x32_bf16 v[52:55], v[228:231], v[36:39], v[52:55]
	v_mfma_f32_16x16x32_bf16 v[44:47], v[228:231], v[236:239], v[216:219]
	ds_read_b128 v[36:39], v72 offset:16384
	s_nop 1
	ds_read_b128 v[216:219], v72 offset:20480
	s_waitcnt lgkmcnt(1)
	v_mfma_f32_16x16x32_bf16 v[32:35], v[4:7], v[36:39], v[208:211]
	s_waitcnt lgkmcnt(0)
	v_mfma_f32_16x16x32_bf16 v[16:19], v[4:7], v[216:219], v[212:215]
	s_nop 0
	ds_read_b128 v[208:211], v72 offset:24576
	s_nop 0
	ds_read_b128 v[212:215], v72 offset:28672
	s_waitcnt lgkmcnt(1)
	v_mfma_f32_16x16x32_bf16 v[8:11], v[4:7], v[208:211], v[224:227]
	s_waitcnt lgkmcnt(0)
	v_mfma_f32_16x16x32_bf16 v[0:3], v[4:7], v[212:215], v[12:15]
	v_mfma_f32_16x16x32_bf16 v[36:39], v[228:231], v[36:39], v[20:23]
	v_mfma_f32_16x16x32_bf16 v[20:23], v[228:231], v[216:219], v[194:197]
	v_mfma_f32_16x16x32_bf16 v[12:15], v[228:231], v[208:211], v[204:207]
	v_mfma_f32_16x16x32_bf16 v[4:7], v[228:231], v[212:215], v[220:223]
	v_ashrrev_i32_e32 v167, 31, v166
	s_waitcnt vmcnt(20)
	v_lshlrev_b32_e32 v228, 16, v24
	v_and_b32_e32 v229, 0xffff0000, v24
	v_lshlrev_b32_e32 v232, 16, v25
	v_and_b32_e32 v233, 0xffff0000, v25
	v_lshl_add_u64 v[24:25], v[166:167], 2, s[0:1]
	global_load_dword v194, v[116:117], off
	global_load_dword v240, v[116:117], off offset:64
	global_load_dword v241, v[116:117], off offset:128
	global_load_dword v242, v[116:117], off offset:192
	global_load_dword v243, v[116:117], off offset:256
	global_load_dword v244, v[116:117], off offset:320
	global_load_dword v245, v[116:117], off offset:384
	global_load_dword v246, v[116:117], off offset:448
	v_lshlrev_b32_e32 v218, 16, v30
	v_and_b32_e32 v219, 0xffff0000, v30
	v_lshlrev_b32_e32 v220, 16, v28
	v_and_b32_e32 v221, 0xffff0000, v28
	v_lshlrev_b32_e32 v222, 16, v31
	v_and_b32_e32 v223, 0xffff0000, v31
	v_lshlrev_b32_e32 v224, 16, v29
	v_and_b32_e32 v225, 0xffff0000, v29
	v_lshlrev_b32_e32 v226, 16, v26
	v_and_b32_e32 v227, 0xffff0000, v26
	v_lshlrev_b32_e32 v230, 16, v27
	v_and_b32_e32 v231, 0xffff0000, v27
	global_load_dwordx4 v[28:31], v[24:25], off
	s_nop 0
	global_load_dwordx4 v[24:27], v[24:25], off offset:64
	v_lshlrev_b32_e32 v196, 16, v174
	v_and_b32_e32 v197, 0xffff0000, v174
	v_lshlrev_b32_e32 v198, 16, v172
	v_and_b32_e32 v199, 0xffff0000, v172
	v_lshlrev_b32_e32 v174, 16, v175
	v_and_b32_e32 v175, 0xffff0000, v175
	v_lshlrev_b32_e32 v172, 16, v173
	v_and_b32_e32 v173, 0xffff0000, v173
	v_lshlrev_b32_e32 v204, 16, v170
	v_and_b32_e32 v205, 0xffff0000, v170
	v_lshlrev_b32_e32 v206, 16, v168
	v_and_b32_e32 v207, 0xffff0000, v168
	v_lshlrev_b32_e32 v170, 16, v171
	v_and_b32_e32 v171, 0xffff0000, v171
	v_lshlrev_b32_e32 v168, 16, v169
	v_and_b32_e32 v169, 0xffff0000, v169
	v_mov_b32_e32 v195, v73
	v_pk_mul_f32 v[166:167], v[198:199], v[196:197]
	v_pk_mul_f32 v[172:173], v[172:173], v[174:175]
	v_pk_mul_f32 v[174:175], v[206:207], v[204:205]
	v_pk_mul_f32 v[168:169], v[168:169], v[170:171]
	v_add_u32_e32 v72, v183, v188
	v_lshl_add_u64 v[170:171], v[72:73], 1, v[114:115]
	v_lshlrev_b32_e32 v208, 16, v164
	v_and_b32_e32 v209, 0xffff0000, v164
	v_lshlrev_b32_e32 v210, 16, v162
	v_and_b32_e32 v211, 0xffff0000, v162
	v_lshlrev_b32_e32 v164, 16, v165
	v_and_b32_e32 v165, 0xffff0000, v165
	v_lshlrev_b32_e32 v162, 16, v163
	v_and_b32_e32 v163, 0xffff0000, v163
	v_lshlrev_b32_e32 v212, 16, v160
	v_and_b32_e32 v213, 0xffff0000, v160
	v_lshlrev_b32_e32 v214, 16, v158
	v_and_b32_e32 v215, 0xffff0000, v158
	v_lshlrev_b32_e32 v160, 16, v161
	v_and_b32_e32 v161, 0xffff0000, v161
	v_lshlrev_b32_e32 v158, 16, v159
	v_and_b32_e32 v159, 0xffff0000, v159
	v_pk_mul_f32 v[196:197], v[210:211], v[208:209]
	v_pk_mul_f32 v[162:163], v[162:163], v[164:165]
	v_pk_mul_f32 v[164:165], v[214:215], v[212:213]
	v_pk_mul_f32 v[158:159], v[158:159], v[160:161]
	v_mov_b32_e32 v217, v73
	v_add_u32_e32 v216, 0x4000, v72
	v_lshl_add_u64 v[160:161], v[216:217], 1, v[114:115]
	s_waitcnt vmcnt(28)
; __device__ __forceinline__ float bflo(unsigned w) { return __uint_as_float(w << 16); }
; __device__ __forceinline__ float bfhi(unsigned w) { return __uint_as_float(w & 0xffff0000u); }
; __device__ __forceinline__ u32x2 pk4(float a, float b, float c, float d) { return u32x2{cvtpk(a, b), cvtpk(c, d)}; }
; __device__ __forceinline__ void phase_sgu(const Params& p, char* shm) {
;     ...
;       const float4 gj0 = *(const float4*)(p.sgu_norm_g + cbase), gj1 = *(const float4*)(p.sgu_norm_g + cbase + 16);
; #pragma unroll
;       for (int nb = 0; nb < 8; ++nb) {
;         const int pp = nb * 16 + fr; const float bias = p.b_s[g * 128 + pp];
;         const u32x2 u0 = uw0[nb], g0 = gw0[nb], u1 = uw1[nb], g1 = gw1[nb];
;         const u32x2 o0 = pk4(bflo(g0[0]) * bflo(u0[0]) * (gj0.x * acc[0][nb][0] + bias), bfhi(g0[0]) * bfhi(u0[0]) * (gj0.y * acc[0][nb][1] + bias),
;                              bflo(g0[1]) * bflo(u0[1]) * (gj0.z * acc[0][nb][2] + bias), bfhi(g0[1]) * bfhi(u0[1]) * (gj0.w * acc[0][nb][3] + bias));
;         const u32x2 o1 = pk4(bflo(g1[0]) * bflo(u1[0]) * (gj1.x * acc[1][nb][0] + bias), bfhi(g1[0]) * bfhi(u1[0]) * (gj1.y * acc[1][nb][1] + bias),
;                              bflo(g1[1]) * bflo(u1[1]) * (gj1.z * acc[1][nb][2] + bias), bfhi(g1[1]) * bfhi(u1[1]) * (gj1.w * acc[1][nb][3] + bias));
;         st_pair16(gbc + (unsigned)(pp * DM + g * 128 + half * 32), fq, o0, o1);
;       }
	v_lshlrev_b32_e32 v234, 16, v156
	v_and_b32_e32 v235, 0xffff0000, v156
	v_lshlrev_b32_e32 v236, 16, v154
	v_and_b32_e32 v237, 0xffff0000, v154
	v_add_u32_e32 v192, 1, v192
	v_cmp_ge_i32_e32 vcc, v192, v180
	v_add_u32_e32 v191, 0x1000, v191
	v_add_u32_e32 v188, 32, v188
	v_add_u32_e32 v189, 32, v189
	v_add_u32_e32 v190, 32, v190
	s_or_b64 s[10:11], vcc, s[10:11]
	s_waitcnt vmcnt(1)
	v_pk_fma_f32 v[64:65], v[64:65], v[28:29], v[194:195] op_sel_hi:[1,1,0]
	v_pk_fma_f32 v[66:67], v[66:67], v[30:31], v[194:195] op_sel_hi:[1,1,0]
	s_waitcnt vmcnt(0)
	v_pk_fma_f32 v[68:69], v[68:69], v[24:25], v[194:195] op_sel_hi:[1,1,0]
	v_pk_fma_f32 v[70:71], v[70:71], v[26:27], v[194:195] op_sel_hi:[1,1,0]
	v_pk_mul_f32 v[64:65], v[166:167], v[64:65]
	v_pk_mul_f32 v[66:67], v[172:173], v[66:67]
	v_pk_mul_f32 v[68:69], v[174:175], v[68:69]
	v_pk_mul_f32 v[70:71], v[168:169], v[70:71]
	v_cvt_pk_bf16_f32 v64, v64, v65
	v_cvt_pk_bf16_f32 v65, v66, v67
	v_cvt_pk_bf16_f32 v66, v68, v69
	v_cvt_pk_bf16_f32 v67, v70, v71
	s_nop 0
	v_permlane16_swap_b32_e32 v64, v66
	v_permlane16_swap_b32_e32 v65, v67
	global_store_dwordx4 v[170:171], v[64:67], off
	s_nop 1
	v_mov_b32_e32 v64, v240
	v_add_u32_e32 v194, 0x8000, v72
	v_lshl_add_u64 v[66:67], v[194:195], 1, v[114:115]
	v_pk_fma_f32 v[56:57], v[56:57], v[28:29], v[64:65] op_sel_hi:[1,1,0]
	v_pk_fma_f32 v[58:59], v[58:59], v[30:31], v[64:65] op_sel_hi:[1,1,0]
	v_pk_fma_f32 v[60:61], v[60:61], v[24:25], v[64:65] op_sel_hi:[1,1,0]
	v_pk_fma_f32 v[62:63], v[62:63], v[26:27], v[64:65] op_sel_hi:[1,1,0]
	v_pk_mul_f32 v[56:57], v[196:197], v[56:57]
	v_pk_mul_f32 v[58:59], v[162:163], v[58:59]
	v_pk_mul_f32 v[60:61], v[164:165], v[60:61]
	v_pk_mul_f32 v[62:63], v[158:159], v[62:63]
	v_cvt_pk_bf16_f32 v56, v56, v57
	v_cvt_pk_bf16_f32 v57, v58, v59
	v_cvt_pk_bf16_f32 v58, v60, v61
	v_cvt_pk_bf16_f32 v59, v62, v63
	s_nop 0
	v_permlane16_swap_b32_e32 v56, v58
	v_permlane16_swap_b32_e32 v57, v59
	global_store_dwordx4 v[160:161], v[56:59], off
	s_nop 1
	v_mov_b32_e32 v56, v241
	v_pk_mul_f32 v[60:61], v[224:225], v[222:223]
	v_pk_mul_f32 v[58:59], v[220:221], v[218:219]
	v_pk_mul_f32 v[62:63], v[228:229], v[226:227]
	v_pk_mul_f32 v[64:65], v[232:233], v[230:231]
	v_pk_fma_f32 v[48:49], v[48:49], v[28:29], v[56:57] op_sel_hi:[1,1,0]
	v_pk_fma_f32 v[50:51], v[50:51], v[30:31], v[56:57] op_sel_hi:[1,1,0]
	v_pk_fma_f32 v[52:53], v[52:53], v[24:25], v[56:57] op_sel_hi:[1,1,0]
	v_pk_fma_f32 v[54:55], v[54:55], v[26:27], v[56:57] op_sel_hi:[1,1,0]
	v_pk_mul_f32 v[48:49], v[58:59], v[48:49]
	v_pk_mul_f32 v[50:51], v[60:61], v[50:51]
	v_pk_mul_f32 v[52:53], v[62:63], v[52:53]
	v_pk_mul_f32 v[54:55], v[64:65], v[54:55]
	v_cvt_pk_bf16_f32 v48, v48, v49
	v_cvt_pk_bf16_f32 v49, v50, v51
	v_cvt_pk_bf16_f32 v50, v52, v53
	v_cvt_pk_bf16_f32 v51, v54, v55
	s_nop 0
	v_permlane16_swap_b32_e32 v48, v50
	v_permlane16_swap_b32_e32 v49, v51
	global_store_dwordx4 v[66:67], v[48:51], off
	s_nop 1
	v_mov_b32_e32 v48, v242
	v_lshlrev_b32_e32 v52, 16, v155
	v_lshlrev_b32_e32 v50, 16, v157
	v_and_b32_e32 v51, 0xffff0000, v157
	v_and_b32_e32 v53, 0xffff0000, v155
	v_lshlrev_b32_e32 v54, 16, v152
	v_and_b32_e32 v55, 0xffff0000, v152
	v_lshlrev_b32_e32 v56, 16, v150
	v_and_b32_e32 v57, 0xffff0000, v150
	v_lshlrev_b32_e32 v58, 16, v153
	v_and_b32_e32 v59, 0xffff0000, v153
	v_lshlrev_b32_e32 v60, 16, v151
	v_and_b32_e32 v61, 0xffff0000, v151
	v_pk_mul_f32 v[64:65], v[236:237], v[234:235]
	v_pk_mul_f32 v[50:51], v[52:53], v[50:51]
	v_pk_mul_f32 v[52:53], v[56:57], v[54:55]
	v_pk_mul_f32 v[54:55], v[60:61], v[58:59]
	v_mov_b32_e32 v63, v73
	v_add_u32_e32 v62, 0xc000, v72
	v_lshl_add_u64 v[56:57], v[62:63], 1, v[114:115]
	v_mov_b32_e32 v59, v73
	v_add_u32_e32 v58, 0x10000, v72
	v_pk_fma_f32 v[40:41], v[40:41], v[28:29], v[48:49] op_sel_hi:[1,1,0]
	v_pk_fma_f32 v[42:43], v[42:43], v[30:31], v[48:49] op_sel_hi:[1,1,0]
	v_pk_fma_f32 v[44:45], v[44:45], v[24:25], v[48:49] op_sel_hi:[1,1,0]
	v_pk_fma_f32 v[46:47], v[46:47], v[26:27], v[48:49] op_sel_hi:[1,1,0]
	v_pk_mul_f32 v[40:41], v[64:65], v[40:41]
	v_pk_mul_f32 v[42:43], v[50:51], v[42:43]
	v_pk_mul_f32 v[44:45], v[52:53], v[44:45]
	v_pk_mul_f32 v[46:47], v[54:55], v[46:47]
	v_cvt_pk_bf16_f32 v40, v40, v41
	v_cvt_pk_bf16_f32 v41, v42, v43
	v_cvt_pk_bf16_f32 v42, v44, v45
	v_cvt_pk_bf16_f32 v43, v46, v47
	s_nop 0
	v_permlane16_swap_b32_e32 v40, v42
	v_permlane16_swap_b32_e32 v41, v43
	global_store_dwordx4 v[56:57], v[40:43], off
	s_nop 1
	v_mov_b32_e32 v40, v243
	v_lshlrev_b32_e32 v44, 16, v146
	v_lshlrev_b32_e32 v42, 16, v148
	v_and_b32_e32 v43, 0xffff0000, v148
	v_and_b32_e32 v45, 0xffff0000, v146
	v_lshlrev_b32_e32 v46, 16, v149
	v_and_b32_e32 v47, 0xffff0000, v149
	v_lshlrev_b32_e32 v48, 16, v147
	v_and_b32_e32 v49, 0xffff0000, v147
	v_lshlrev_b32_e32 v50, 16, v144
	v_and_b32_e32 v51, 0xffff0000, v144
	v_lshlrev_b32_e32 v52, 16, v142
	v_and_b32_e32 v53, 0xffff0000, v142
	v_lshlrev_b32_e32 v54, 16, v145
	v_and_b32_e32 v55, 0xffff0000, v145
	v_lshlrev_b32_e32 v56, 16, v143
	v_and_b32_e32 v57, 0xffff0000, v143
	v_pk_mul_f32 v[42:43], v[44:45], v[42:43]
	v_pk_mul_f32 v[44:45], v[48:49], v[46:47]
	v_pk_mul_f32 v[46:47], v[52:53], v[50:51]
	v_pk_mul_f32 v[48:49], v[56:57], v[54:55]
	v_lshl_add_u64 v[50:51], v[58:59], 1, v[114:115]
	v_pk_fma_f32 v[32:33], v[32:33], v[28:29], v[40:41] op_sel_hi:[1,1,0]
	v_pk_fma_f32 v[34:35], v[34:35], v[30:31], v[40:41] op_sel_hi:[1,1,0]
; __device__ __forceinline__ void phase_sgu(const Params& p, char* shm) {
;     ...
;   for (int item = blockIdx.x; item < T_TOK / 64; item += gridDim.x) {
;     const int chunk = item >> 1, hh = item & 1, g = hh * 4 + g4;
;     if (hh != loaded_hh) {
;       __syncthreads();
;       const char* src = (const char*)((const u16*)(p.ws + OFF_WS) + hh * 4 * 16384);
; #pragma unroll 4
;       for (int k = 0; k < 16; ++k) {
;         const int byte = (tid + k * 512) * 16, pr = (byte >> 8) & 15;
;         *(u32x4*)(shm + (byte & ~255) + ((byte & 255) ^ (pr << 4))) = *(const u32x4*)(src + byte);
;       }
;       __syncthreads(); loaded_hh = hh;
;     }
;     float sc[4][8];
; #pragma unroll
;     for (int ks = 0; ks < 4; ++ks) {
;       const float4 s0 = *(const float4*)(ssq_vs + chunk * 128 + ks * 32 + fq * 8), s1 = *(const float4*)(ssq_vs + chunk * 128 + ks * 32 + fq * 8 + 4);
;       sc[ks][0] = rsqrtf(s0.x * (1.f / DM) + EPS); sc[ks][1] = rsqrtf(s0.y * (1.f / DM) + EPS); sc[ks][2] = rsqrtf(s0.z * (1.f / DM) + EPS); sc[ks][3] = rsqrtf(s0.w * (1.f / DM) + EPS);
;       sc[ks][4] = rsqrtf(s1.x * (1.f / DM) + EPS); sc[ks][5] = rsqrtf(s1.y * (1.f / DM) + EPS); sc[ks][6] = rsqrtf(s1.z * (1.f / DM) + EPS); sc[ks][7] = rsqrtf(s1.w * (1.f / DM) + EPS);
;     }
;     const u16* ubc = ub + (long)chunk * 128 * DM; u16* gbc = gb + (long)chunk * 128 * DM;
; #pragma unroll 1
;     for (int half = (wv >> 2) * 2; half < (wv >> 2) * 2 + 2; ++half) {
;     ...
; #pragma unroll
;       for (int nb = 0; nb < 8; ++nb) {
;         const int pp = nb * 16 + fr; const float bias = p.b_s[g * 128 + pp];
;         const u32x2 u0 = uw0[nb], g0 = gw0[nb], u1 = uw1[nb], g1 = gw1[nb];
;         const u32x2 o0 = pk4(bflo(g0[0]) * bflo(u0[0]) * (gj0.x * acc[0][nb][0] + bias), bfhi(g0[0]) * bfhi(u0[0]) * (gj0.y * acc[0][nb][1] + bias),
;                              bflo(g0[1]) * bflo(u0[1]) * (gj0.z * acc[0][nb][2] + bias), bfhi(g0[1]) * bfhi(u0[1]) * (gj0.w * acc[0][nb][3] + bias));
;         const u32x2 o1 = pk4(bflo(g1[0]) * bflo(u1[0]) * (gj1.x * acc[1][nb][0] + bias), bfhi(g1[0]) * bfhi(u1[0]) * (gj1.y * acc[1][nb][1] + bias),
;                              bflo(g1[1]) * bflo(u1[1]) * (gj1.z * acc[1][nb][2] + bias), bfhi(g1[1]) * bfhi(u1[1]) * (gj1.w * acc[1][nb][3] + bias));
;         st_pair16(gbc + (unsigned)(pp * DM + g * 128 + half * 32), fq, o0, o1);
;       }
	v_pk_fma_f32 v[36:37], v[36:37], v[24:25], v[40:41] op_sel_hi:[1,1,0]
	v_pk_fma_f32 v[38:39], v[38:39], v[26:27], v[40:41] op_sel_hi:[1,1,0]
	v_pk_mul_f32 v[32:33], v[42:43], v[32:33]
	v_pk_mul_f32 v[34:35], v[44:45], v[34:35]
	v_pk_mul_f32 v[36:37], v[46:47], v[36:37]
	v_pk_mul_f32 v[38:39], v[48:49], v[38:39]
	v_cvt_pk_bf16_f32 v32, v32, v33
	v_cvt_pk_bf16_f32 v33, v34, v35
	v_cvt_pk_bf16_f32 v34, v36, v37
	v_cvt_pk_bf16_f32 v35, v38, v39
	s_nop 0
	v_permlane16_swap_b32_e32 v32, v34
	v_permlane16_swap_b32_e32 v33, v35
	global_store_dwordx4 v[50:51], v[32:35], off
	s_nop 1
	v_mov_b32_e32 v32, v244
	v_lshlrev_b32_e32 v36, 16, v138
	v_lshlrev_b32_e32 v34, 16, v140
	v_and_b32_e32 v35, 0xffff0000, v140
	v_and_b32_e32 v37, 0xffff0000, v138
	v_lshlrev_b32_e32 v38, 16, v141
	v_and_b32_e32 v39, 0xffff0000, v141
	v_lshlrev_b32_e32 v40, 16, v139
	v_and_b32_e32 v41, 0xffff0000, v139
	v_lshlrev_b32_e32 v42, 16, v136
	v_and_b32_e32 v43, 0xffff0000, v136
	v_lshlrev_b32_e32 v44, 16, v134
	v_and_b32_e32 v45, 0xffff0000, v134
	v_lshlrev_b32_e32 v46, 16, v137
	v_and_b32_e32 v47, 0xffff0000, v137
	v_lshlrev_b32_e32 v48, 16, v135
	v_and_b32_e32 v49, 0xffff0000, v135
	v_pk_mul_f32 v[34:35], v[36:37], v[34:35]
	v_pk_mul_f32 v[36:37], v[40:41], v[38:39]
	v_pk_mul_f32 v[38:39], v[44:45], v[42:43]
	v_pk_mul_f32 v[40:41], v[48:49], v[46:47]
	v_mov_b32_e32 v51, v73
	v_add_u32_e32 v50, 0x14000, v72
	v_lshl_add_u64 v[42:43], v[50:51], 1, v[114:115]
	v_pk_fma_f32 v[16:17], v[16:17], v[28:29], v[32:33] op_sel_hi:[1,1,0]
	v_pk_fma_f32 v[18:19], v[18:19], v[30:31], v[32:33] op_sel_hi:[1,1,0]
	v_pk_fma_f32 v[20:21], v[20:21], v[24:25], v[32:33] op_sel_hi:[1,1,0]
	v_pk_fma_f32 v[22:23], v[22:23], v[26:27], v[32:33] op_sel_hi:[1,1,0]
	v_pk_mul_f32 v[16:17], v[34:35], v[16:17]
	v_pk_mul_f32 v[18:19], v[36:37], v[18:19]
	v_pk_mul_f32 v[20:21], v[38:39], v[20:21]
	v_pk_mul_f32 v[22:23], v[40:41], v[22:23]
	v_cvt_pk_bf16_f32 v16, v16, v17
	v_cvt_pk_bf16_f32 v17, v18, v19
	v_cvt_pk_bf16_f32 v18, v20, v21
	v_cvt_pk_bf16_f32 v19, v22, v23
	s_nop 0
	v_permlane16_swap_b32_e32 v16, v18
	v_permlane16_swap_b32_e32 v17, v19
	global_store_dwordx4 v[42:43], v[16:19], off
	s_nop 1
	v_mov_b32_e32 v16, v245
	v_lshlrev_b32_e32 v20, 16, v130
	v_lshlrev_b32_e32 v18, 16, v132
	v_and_b32_e32 v19, 0xffff0000, v132
	v_and_b32_e32 v21, 0xffff0000, v130
	v_lshlrev_b32_e32 v22, 16, v133
	v_and_b32_e32 v23, 0xffff0000, v133
	v_lshlrev_b32_e32 v32, 16, v131
	v_and_b32_e32 v33, 0xffff0000, v131
	v_lshlrev_b32_e32 v34, 16, v128
	v_and_b32_e32 v35, 0xffff0000, v128
	v_lshlrev_b32_e32 v36, 16, v126
	v_and_b32_e32 v37, 0xffff0000, v126
	v_lshlrev_b32_e32 v38, 16, v129
	v_and_b32_e32 v39, 0xffff0000, v129
	v_lshlrev_b32_e32 v40, 16, v127
	v_and_b32_e32 v41, 0xffff0000, v127
	v_pk_mul_f32 v[18:19], v[20:21], v[18:19]
	v_pk_mul_f32 v[20:21], v[32:33], v[22:23]
	v_pk_mul_f32 v[22:23], v[36:37], v[34:35]
	v_pk_mul_f32 v[32:33], v[40:41], v[38:39]
	v_mov_b32_e32 v43, v73
	v_add_u32_e32 v42, 0x18000, v72
	v_lshl_add_u64 v[34:35], v[42:43], 1, v[114:115]
	v_add_u32_e32 v72, 0x1c000, v72
	v_pk_fma_f32 v[8:9], v[8:9], v[28:29], v[16:17] op_sel_hi:[1,1,0]
	v_pk_fma_f32 v[10:11], v[10:11], v[30:31], v[16:17] op_sel_hi:[1,1,0]
	v_pk_fma_f32 v[12:13], v[12:13], v[24:25], v[16:17] op_sel_hi:[1,1,0]
	v_pk_fma_f32 v[14:15], v[14:15], v[26:27], v[16:17] op_sel_hi:[1,1,0]
	v_pk_mul_f32 v[8:9], v[18:19], v[8:9]
	v_pk_mul_f32 v[10:11], v[20:21], v[10:11]
	v_pk_mul_f32 v[12:13], v[22:23], v[12:13]
	v_pk_mul_f32 v[14:15], v[32:33], v[14:15]
	v_cvt_pk_bf16_f32 v8, v8, v9
	v_cvt_pk_bf16_f32 v9, v10, v11
	v_cvt_pk_bf16_f32 v10, v12, v13
	v_cvt_pk_bf16_f32 v11, v14, v15
	s_nop 0
	v_permlane16_swap_b32_e32 v8, v10
	v_permlane16_swap_b32_e32 v9, v11
	global_store_dwordx4 v[34:35], v[8:11], off
	s_nop 1
	v_mov_b32_e32 v8, v246
	v_lshlrev_b32_e32 v12, 16, v122
	v_lshlrev_b32_e32 v10, 16, v124
	v_and_b32_e32 v11, 0xffff0000, v124
	v_and_b32_e32 v13, 0xffff0000, v122
	v_lshlrev_b32_e32 v14, 16, v125
	v_and_b32_e32 v15, 0xffff0000, v125
	v_lshlrev_b32_e32 v16, 16, v123
	v_and_b32_e32 v17, 0xffff0000, v123
	v_lshlrev_b32_e32 v18, 16, v120
	v_and_b32_e32 v19, 0xffff0000, v120
	v_lshlrev_b32_e32 v20, 16, v118
	v_and_b32_e32 v21, 0xffff0000, v118
	v_lshlrev_b32_e32 v22, 16, v121
	v_and_b32_e32 v23, 0xffff0000, v121
	v_lshlrev_b32_e32 v32, 16, v119
	v_and_b32_e32 v33, 0xffff0000, v119
	v_pk_mul_f32 v[10:11], v[12:13], v[10:11]
	v_pk_mul_f32 v[12:13], v[16:17], v[14:15]
	v_pk_mul_f32 v[14:15], v[20:21], v[18:19]
	v_pk_mul_f32 v[16:17], v[32:33], v[22:23]
	v_lshl_add_u64 v[18:19], v[72:73], 1, v[114:115]
	v_pk_fma_f32 v[0:1], v[0:1], v[28:29], v[8:9] op_sel_hi:[1,1,0]
	v_pk_fma_f32 v[2:3], v[2:3], v[30:31], v[8:9] op_sel_hi:[1,1,0]
	v_pk_fma_f32 v[4:5], v[4:5], v[24:25], v[8:9] op_sel_hi:[1,1,0]
	v_pk_fma_f32 v[6:7], v[6:7], v[26:27], v[8:9] op_sel_hi:[1,1,0]
	v_pk_mul_f32 v[0:1], v[10:11], v[0:1]
	v_pk_mul_f32 v[2:3], v[12:13], v[2:3]
	v_pk_mul_f32 v[4:5], v[14:15], v[4:5]
	v_pk_mul_f32 v[6:7], v[16:17], v[6:7]
	v_cvt_pk_bf16_f32 v0, v0, v1
	v_cvt_pk_bf16_f32 v1, v2, v3
	v_cvt_pk_bf16_f32 v2, v4, v5
	v_cvt_pk_bf16_f32 v3, v6, v7
	s_nop 0
	v_permlane16_swap_b32_e32 v0, v2
	v_permlane16_swap_b32_e32 v1, v3
	global_store_dwordx4 v[18:19], v[0:3], off
	s_andn2_b64 exec, exec, s[10:11]
	s_cbranch_execnz .LBB0_217
	s_or_b64 exec, exec, s[10:11]
	s_add_i32 s76, s76, s28
	s_xor_b64 s[64:65], s[64:65], s[68:69]
	s_cmpk_gt_i32 s76, 0x4ff
	s_cbranch_scc0 .LBB0_212
